# stack + P3 block start: list-length and first routed entry loaded before the LDS barriers; K/V prefetch no longer drained before the first group
# baseline (speedup 1.0000x reference)
.LBB0_379:
	s_add_i32 s100, s42, s3
	s_ashr_i32 s101, s100, 31
	s_lshl_b64 s[100:101], s[100:101], 2
	s_add_u32 s100, s20, s100
	s_addc_u32 s101, s21, s101
	v_mov_b32_e32 v249, 0
	global_load_dword v249, v249, s[100:101]
	s_add_i32 s98, s42, -1
	s_mul_i32 s98, s98, s42
	s_lshr_b32 s98, s98, 1
	s_mul_i32 s99, s42, 31
	s_sub_i32 s98, s99, s98
	s_lshl_b32 s98, s98, 8
	s_mov_b32 s99, 0
	s_lshl_b64 s[98:99], s[98:99], 2
	s_add_u32 s98, s55, s98
	s_addc_u32 s99, s41, s99
	v_mov_b32_e32 v252, v201
	v_mov_b32_e32 v253, 0
	v_lshl_add_u64 v[252:253], v[252:253], 2, s[98:99]
	global_load_dword v254, v[252:253], off
	s_waitcnt lgkmcnt(0)
	s_barrier
	s_waitcnt vmcnt(11)
	ds_write_b128 v223, v[68:71]
	s_waitcnt vmcnt(10)
	ds_write_b128 v224, v[64:67] offset:36864
	s_waitcnt vmcnt(9)
	ds_write_b128 v225, v[76:79]
	s_waitcnt vmcnt(8)
	ds_write_b128 v226, v[72:75] offset:36864
	s_waitcnt vmcnt(7)
	ds_write_b128 v227, v[84:87]
	s_waitcnt vmcnt(6)
	ds_write_b128 v228, v[80:83] offset:36864
	s_waitcnt vmcnt(5)
	ds_write_b128 v229, v[92:95]
	s_waitcnt vmcnt(4)
	ds_write_b128 v230, v[88:91] offset:36864
	s_waitcnt lgkmcnt(0)
	s_barrier
	s_waitcnt vmcnt(0)
	s_cmp_gt_i32 s57, -1
	s_mov_b64 s[0:1], -1
	s_cbranch_scc1 .LBB0_381
	s_lshl_b32 s58, s42, 8
	s_mov_b64 s[0:1], 0

.LBB0_383:
	v_mov_b32_e32 v195, 0
	s_add_i32 s1, s42, -1
	s_mul_i32 s1, s1, s42
	s_mul_i32 s0, s42, 31
	s_lshr_b32 s42, s1, 31
	s_add_i32 s1, s1, s42
	s_lshr_b32 s1, s1, 1
	s_sub_i32 s0, s0, s1
	s_lshl_b32 s0, s0, 8
	s_ashr_i32 s1, s0, 31
	s_lshl_b64 s[0:1], s[0:1], 2
	s_mov_b64 s[82:83], 0
	v_readfirstlane_b32 s42, v249
	s_add_i32 s57, s42, 0x100
	s_addk_i32 s42, 0x11f
	s_ashr_i32 s42, s42, 5
	s_add_u32 s78, s55, s0
	s_addc_u32 s79, s41, s1
	s_cmp_ge_i32 s27, s42
	s_cbranch_scc1 .LBB0_385
	v_cmp_gt_i32_e32 vcc, s57, v200
	s_and_b64 s[82:83], vcc, exec
	s_nop 0
	v_cndmask_b32_e32 v195, 0, v254, vcc
.LBB0_385:
	s_cmp_ge_i32 s89, s42
	s_cbranch_scc1 .LBB0_406
	v_and_b32_e32 v1, 64, v232
	v_xor_b32_e32 v0, 32, v232
	v_add_u32_e32 v2, 64, v1
	v_cmp_lt_i32_e32 vcc, v0, v2
	v_add_u32_e32 v194, s58, v199
	v_add_u32_e32 v187, s8, v199
	v_cndmask_b32_e32 v0, v232, v0, vcc
	v_lshlrev_b32_e32 v238, 2, v0
	v_or_b32_e32 v0, v1, v219
	v_lshlrev_b32_e32 v239, 2, v0
	s_mov_b64 s[80:81], -1
	v_mov_b32_e32 v196, 3
	v_mov_b32_e32 v240, v171
	v_mov_b32_e32 v241, v202
	s_mov_b32 s58, s89
	s_mov_b32 s100, 1
.LBB0_387:
	s_add_i32 s8, s58, 8
	s_cmp_ge_i32 s8, s42
	s_cselect_b64 s[84:85], -1, 0
	s_cmp_lg_u32 s100, 0
	s_cbranch_scc1 .Lp3_skipw
	s_waitcnt vmcnt(0)
.Lp3_skipw:
	s_mov_b32 s100, 0
	s_cmp_lt_i32 s8, s42
	v_and_b32_e32 v242, 0x1fff, v195
	s_cselect_b64 vcc, -1, 0
	v_cndmask_b32_e32 v0, v187, v242, vcc
	v_ashrrev_i32_e32 v1, 31, v0
	v_lshlrev_b64 v[0:1], 11, v[0:1]
	v_lshl_add_u64 v[0:1], v[188:189], 0, v[0:1]
	global_load_dwordx4 v[124:127], v[0:1], off
	global_load_dwordx4 v[120:123], v[0:1], off offset:32
	global_load_dwordx4 v[116:119], v[0:1], off offset:64
	global_load_dwordx4 v[112:115], v[0:1], off offset:96
	s_add_i32 s0, s58, 16
	s_cmp_ge_i32 s0, s42
	s_cbranch_scc1 .LBB0_389
	v_add_u32_e32 v0, s88, v240
	v_add_u32_e32 v1, 0x200, v0
	v_add_u32_e32 v0, 0x100, v0
	v_cmp_gt_i32_e32 vcc, s57, v1
	s_and_b64 s[86:87], vcc, exec
	s_nop 0
	v_cndmask_b32_e32 v162, 0, v0, vcc
	v_lshl_add_u64 v[0:1], v[162:163], 2, s[78:79]
	global_load_dword v243, v[0:1], off
	s_branch .LBB0_390
